# v108 + fused final epilogue pass 1: rolling 4-deep prefetch of stream-tile pieces with counted vmcnt
# speedup vs baseline: 1.0035x; 1.0030x over previous
.LBB0_1357:
	v_and_b32_e32 v135, 64, v235
	v_xor_b32_e32 v134, 16, v235
	v_add_u32_e32 v135, 64, v135
	v_cmp_lt_i32_e32 vcc, v134, v135
	v_lshl_add_u32 v156, s16, 8, v193
	v_lshl_or_b32 v150, s17, 8, v195
	v_cndmask_b32_e32 v134, v235, v134, vcc
	v_lshlrev_b32_e32 v197, 2, v134
	v_xor_b32_e32 v134, 32, v235
	v_cmp_lt_i32_e32 vcc, v134, v135
	v_ashrrev_i32_e32 v151, 31, v150
	v_ashrrev_i32_e32 v157, 31, v156
	v_cndmask_b32_e32 v134, v235, v134, vcc
	v_lshl_add_u64 v[132:133], v[150:151], 1, s[8:9]
	v_lshlrev_b32_e32 v149, 2, v134
	v_lshlrev_b64 v[134:135], 13, v[156:157]
	v_lshl_add_u64 v[152:153], v[132:133], 0, v[134:135]
	global_load_dwordx4 v[158:161], v[152:153], off
	global_load_dwordx4 v[162:165], v[152:153], off offset:256
	s_mov_b64 s[100:101], 0x20000
	v_lshl_add_u64 v[250:251], v[152:153], 0, s[100:101]
	global_load_dwordx4 v[220:223], v[250:251], off
	s_mov_b64 s[100:101], 0x20000
	v_lshl_add_u64 v[250:251], v[152:153], 0, s[100:101]
	global_load_dwordx4 v[224:227], v[250:251], off offset:256
	s_mov_b64 s[100:101], 0x40000
	v_lshl_add_u64 v[250:251], v[152:153], 0, s[100:101]
	global_load_dwordx4 v[242:245], v[250:251], off
	s_mov_b64 s[100:101], 0x40000
	v_lshl_add_u64 v[250:251], v[152:153], 0, s[100:101]
	global_load_dwordx4 v[246:249], v[250:251], off offset:256
	v_mov_b32_e32 v166, v126
	v_mov_b32_e32 v167, v118
	v_mov_b32_e32 v168, v127
	v_mov_b32_e32 v169, v119
	v_mov_b32_e32 v170, v128
	v_mov_b32_e32 v171, v120
	v_mov_b32_e32 v172, v123
	v_mov_b32_e32 v173, v115
	v_mov_b32_e32 v174, v124
	v_mov_b32_e32 v175, v116
	v_lshlrev_b64 v[154:155], 12, v[156:157]
	v_cmp_lt_i32_e32 vcc, 1, v192
	s_waitcnt vmcnt(4)
	v_lshlrev_b32_e32 v134, 16, v158
	v_lshlrev_b32_e32 v135, 16, v162
	v_pk_add_f32 v[134:135], v[166:167], v[134:135]
	v_and_b32_e32 v167, 0xffff0000, v162
	v_and_b32_e32 v166, 0xffff0000, v158
	v_pk_add_f32 v[166:167], v[168:169], v[166:167]
	v_lshlrev_b32_e32 v169, 16, v163
	v_lshlrev_b32_e32 v168, 16, v159
	v_and_b32_e32 v163, 0xffff0000, v163
	v_and_b32_e32 v162, 0xffff0000, v159
	v_mov_b32_e32 v158, v129
	v_mov_b32_e32 v159, v121
	v_pk_add_f32 v[168:169], v[170:171], v[168:169]
	v_pk_add_f32 v[158:159], v[158:159], v[162:163]
	v_lshlrev_b32_e32 v163, 16, v164
	v_lshlrev_b32_e32 v162, 16, v160
	v_mov_b32_e32 v170, v122
	v_mov_b32_e32 v171, v114
	v_pk_add_f32 v[162:163], v[170:171], v[162:163]
	v_and_b32_e32 v171, 0xffff0000, v164
	v_and_b32_e32 v170, 0xffff0000, v160
	v_pk_add_f32 v[170:171], v[172:173], v[170:171]
	v_lshlrev_b32_e32 v173, 16, v165
	v_lshlrev_b32_e32 v172, 16, v161
	v_and_b32_e32 v165, 0xffff0000, v165
	v_and_b32_e32 v164, 0xffff0000, v161
	v_mov_b32_e32 v160, v125
	v_mov_b32_e32 v161, v117
	v_pk_add_f32 v[160:161], v[160:161], v[164:165]
	v_pk_mul_f32 v[164:165], v[166:167], v[166:167]
	v_pk_mul_f32 v[158:159], v[158:159], v[158:159]
	v_pk_fma_f32 v[134:135], v[134:135], v[134:135], v[164:165]
	v_pk_fma_f32 v[158:159], v[168:169], v[168:169], v[158:159]
	v_pk_add_f32 v[172:173], v[174:175], v[172:173]
	v_pk_add_f32 v[134:135], v[134:135], v[158:159]
	v_pk_mul_f32 v[158:159], v[170:171], v[170:171]
	v_pk_mul_f32 v[160:161], v[160:161], v[160:161]
	v_pk_fma_f32 v[158:159], v[162:163], v[162:163], v[158:159]
	v_pk_fma_f32 v[160:161], v[172:173], v[172:173], v[160:161]
	v_or_b32_e32 v162, 16, v156
	v_pk_add_f32 v[158:159], v[158:159], v[160:161]
	v_ashrrev_i32_e32 v163, 31, v162
	v_pk_add_f32 v[134:135], v[134:135], v[158:159]
	v_lshlrev_b64 v[160:161], 12, v[162:163]
	v_add_f32_e32 v134, v134, v135
	ds_bpermute_b32 v135, v197, v134
	s_waitcnt lgkmcnt(0)
	v_add_f32_e32 v198, v134, v135
	v_lshlrev_b64 v[134:135], 13, v[162:163]
	v_lshl_add_u64 v[158:159], v[132:133], 0, v[134:135]
	ds_bpermute_b32 v199, v149, v198
	s_waitcnt vmcnt(3)
	v_mov_b32_e32 v164, v220
	v_mov_b32_e32 v165, v221
	v_mov_b32_e32 v166, v222
	v_mov_b32_e32 v167, v223
	s_mov_b64 s[100:101], 0x60000
	v_lshl_add_u64 v[250:251], v[152:153], 0, s[100:101]
	global_load_dwordx4 v[220:223], v[250:251], off
	v_and_b32_e32 v135, 0xffff0000, v164
	v_lshlrev_b32_e32 v134, 16, v164
	v_add_f32_e32 v135, v111, v135
	v_lshlrev_b32_e32 v164, 16, v165
	v_and_b32_e32 v165, 0xffff0000, v165
	v_add_f32_e32 v134, v110, v134
	v_add_f32_e32 v165, v113, v165
	v_mul_f32_e32 v135, v135, v135
	v_add_f32_e32 v164, v112, v164
	v_lshlrev_b32_e32 v168, 16, v166
	v_and_b32_e32 v166, 0xffff0000, v166
	v_lshlrev_b32_e32 v169, 16, v167
	v_and_b32_e32 v167, 0xffff0000, v167
	v_fmac_f32_e32 v135, v134, v134
	v_mul_f32_e32 v134, v165, v165
	v_add_f32_e32 v166, v107, v166
	v_add_f32_e32 v167, v109, v167
	v_fmac_f32_e32 v134, v164, v164
	v_add_f32_e32 v168, v106, v168
	v_add_f32_e32 v169, v108, v169
	v_add_f32_e32 v134, v135, v134
	v_mul_f32_e32 v135, v166, v166
	v_mul_f32_e32 v164, v167, v167
	v_fmac_f32_e32 v135, v168, v168
	v_fmac_f32_e32 v164, v169, v169
	v_add_f32_e32 v135, v135, v164
	v_add_f32_e32 v134, v134, v135
	s_waitcnt vmcnt(3)
	v_mov_b32_e32 v164, v224
	v_mov_b32_e32 v165, v225
	v_mov_b32_e32 v166, v226
	v_mov_b32_e32 v167, v227
	s_mov_b64 s[100:101], 0x60000
	v_lshl_add_u64 v[250:251], v[152:153], 0, s[100:101]
	global_load_dwordx4 v[224:227], v[250:251], off offset:256
	v_lshlrev_b32_e32 v135, 16, v164
	v_and_b32_e32 v164, 0xffff0000, v164
	v_add_f32_e32 v164, v103, v164
	v_lshlrev_b32_e32 v168, 16, v165
	v_and_b32_e32 v165, 0xffff0000, v165
	v_add_f32_e32 v135, v102, v135
	v_add_f32_e32 v165, v105, v165
	v_mul_f32_e32 v164, v164, v164
	v_add_f32_e32 v168, v104, v168
	v_lshlrev_b32_e32 v169, 16, v166
	v_and_b32_e32 v166, 0xffff0000, v166
	v_lshlrev_b32_e32 v170, 16, v167
	v_and_b32_e32 v167, 0xffff0000, v167
	v_fmac_f32_e32 v164, v135, v135
	v_mul_f32_e32 v135, v165, v165
	v_add_f32_e32 v166, v99, v166
	v_add_f32_e32 v167, v101, v167
	v_fmac_f32_e32 v135, v168, v168
	v_add_f32_e32 v169, v98, v169
	v_add_f32_e32 v170, v100, v170
	v_add_f32_e32 v135, v164, v135
	v_mul_f32_e32 v164, v166, v166
	v_mul_f32_e32 v165, v167, v167
	v_fmac_f32_e32 v164, v169, v169
	v_fmac_f32_e32 v165, v170, v170
	v_add_f32_e32 v164, v164, v165
	v_add_f32_e32 v135, v135, v164
	v_add_f32_e32 v134, v134, v135
	ds_bpermute_b32 v135, v197, v134
	v_or_b32_e32 v168, 32, v156
	v_ashrrev_i32_e32 v169, 31, v168
	v_lshlrev_b64 v[166:167], 12, v[168:169]
	s_waitcnt lgkmcnt(0)
	v_add_f32_e32 v200, v134, v135
	v_lshlrev_b64 v[134:135], 13, v[168:169]
	v_lshl_add_u64 v[164:165], v[132:133], 0, v[134:135]
	ds_bpermute_b32 v201, v149, v200
	s_waitcnt vmcnt(3)
	v_mov_b32_e32 v170, v242
	v_mov_b32_e32 v171, v243
	v_mov_b32_e32 v172, v244
	v_mov_b32_e32 v173, v245
	s_mov_b64 s[100:101], 0x100000
	v_lshl_add_u64 v[250:251], v[152:153], 0, s[100:101]
	global_load_dwordx4 v[242:245], v[250:251], off
	v_and_b32_e32 v135, 0xffff0000, v170
	v_lshlrev_b32_e32 v134, 16, v170
	v_add_f32_e32 v135, v95, v135
	v_lshlrev_b32_e32 v170, 16, v171
	v_and_b32_e32 v171, 0xffff0000, v171
	v_add_f32_e32 v134, v94, v134
	v_add_f32_e32 v171, v97, v171
	v_mul_f32_e32 v135, v135, v135
	v_add_f32_e32 v170, v96, v170
	v_lshlrev_b32_e32 v174, 16, v172
	v_and_b32_e32 v172, 0xffff0000, v172
	v_lshlrev_b32_e32 v175, 16, v173
	v_and_b32_e32 v173, 0xffff0000, v173
	v_fmac_f32_e32 v135, v134, v134
	v_mul_f32_e32 v134, v171, v171
	v_add_f32_e32 v172, v91, v172
	v_add_f32_e32 v173, v93, v173
	v_fmac_f32_e32 v134, v170, v170
	v_add_f32_e32 v174, v90, v174
	v_add_f32_e32 v175, v92, v175
	v_add_f32_e32 v134, v135, v134
	v_mul_f32_e32 v135, v172, v172
	v_mul_f32_e32 v170, v173, v173
	v_fmac_f32_e32 v135, v174, v174
	v_fmac_f32_e32 v170, v175, v175
	v_add_f32_e32 v135, v135, v170
	v_add_f32_e32 v134, v134, v135
	s_waitcnt vmcnt(3)
	v_mov_b32_e32 v170, v246
	v_mov_b32_e32 v171, v247
	v_mov_b32_e32 v172, v248
	v_mov_b32_e32 v173, v249
	s_mov_b64 s[100:101], 0x100000
	v_lshl_add_u64 v[250:251], v[152:153], 0, s[100:101]
	global_load_dwordx4 v[246:249], v[250:251], off offset:256
	v_lshlrev_b32_e32 v135, 16, v170
	v_and_b32_e32 v170, 0xffff0000, v170
	v_add_f32_e32 v170, v87, v170
	v_lshlrev_b32_e32 v174, 16, v171
	v_and_b32_e32 v171, 0xffff0000, v171
	v_add_f32_e32 v135, v86, v135
	v_add_f32_e32 v171, v89, v171
	v_mul_f32_e32 v170, v170, v170
	v_add_f32_e32 v174, v88, v174
	v_lshlrev_b32_e32 v175, 16, v172
	v_and_b32_e32 v172, 0xffff0000, v172
	v_lshlrev_b32_e32 v176, 16, v173
	v_and_b32_e32 v173, 0xffff0000, v173
	v_fmac_f32_e32 v170, v135, v135
	v_mul_f32_e32 v135, v171, v171
	v_add_f32_e32 v172, v83, v172
	v_add_f32_e32 v173, v85, v173
	v_fmac_f32_e32 v135, v174, v174
	v_add_f32_e32 v175, v82, v175
	v_add_f32_e32 v176, v84, v176
	v_add_f32_e32 v135, v170, v135
	v_mul_f32_e32 v170, v172, v172
	v_mul_f32_e32 v171, v173, v173
	v_fmac_f32_e32 v170, v175, v175
	v_fmac_f32_e32 v171, v176, v176
	v_add_f32_e32 v170, v170, v171
	v_add_f32_e32 v135, v135, v170
	v_add_f32_e32 v134, v134, v135
	ds_bpermute_b32 v135, v197, v134
	v_or_b32_e32 v174, 48, v156
	v_ashrrev_i32_e32 v175, 31, v174
	v_lshlrev_b64 v[172:173], 12, v[174:175]
	s_waitcnt lgkmcnt(0)
	v_add_f32_e32 v202, v134, v135
	v_lshlrev_b64 v[134:135], 13, v[174:175]
	v_lshl_add_u64 v[170:171], v[132:133], 0, v[134:135]
	ds_bpermute_b32 v203, v149, v202
	s_waitcnt vmcnt(3)
	v_mov_b32_e32 v176, v220
	v_mov_b32_e32 v177, v221
	v_mov_b32_e32 v178, v222
	v_mov_b32_e32 v179, v223
	s_mov_b64 s[100:101], 0x120000
	v_lshl_add_u64 v[250:251], v[152:153], 0, s[100:101]
	global_load_dwordx4 v[220:223], v[250:251], off
	v_and_b32_e32 v135, 0xffff0000, v176
	v_lshlrev_b32_e32 v134, 16, v176
	v_add_f32_e32 v135, v79, v135
	v_lshlrev_b32_e32 v176, 16, v177
	v_and_b32_e32 v177, 0xffff0000, v177
	v_add_f32_e32 v134, v78, v134
	v_add_f32_e32 v177, v81, v177
	v_mul_f32_e32 v135, v135, v135
	v_add_f32_e32 v176, v80, v176
	v_lshlrev_b32_e32 v180, 16, v178
	v_and_b32_e32 v178, 0xffff0000, v178
	v_lshlrev_b32_e32 v181, 16, v179
	v_and_b32_e32 v179, 0xffff0000, v179
	v_fmac_f32_e32 v135, v134, v134
	v_mul_f32_e32 v134, v177, v177
	v_add_f32_e32 v178, v75, v178
	v_add_f32_e32 v179, v77, v179
	v_fmac_f32_e32 v134, v176, v176
	v_add_f32_e32 v180, v74, v180
	v_add_f32_e32 v181, v76, v181
	v_add_f32_e32 v134, v135, v134
	v_mul_f32_e32 v135, v178, v178
	v_mul_f32_e32 v176, v179, v179
	v_fmac_f32_e32 v135, v180, v180
	v_fmac_f32_e32 v176, v181, v181
	v_add_f32_e32 v135, v135, v176
	v_add_f32_e32 v134, v134, v135
	s_waitcnt vmcnt(3)
	v_mov_b32_e32 v176, v224
	v_mov_b32_e32 v177, v225
	v_mov_b32_e32 v178, v226
	v_mov_b32_e32 v179, v227
	s_mov_b64 s[100:101], 0x120000
	v_lshl_add_u64 v[250:251], v[152:153], 0, s[100:101]
	global_load_dwordx4 v[224:227], v[250:251], off offset:256
	v_lshlrev_b32_e32 v135, 16, v176
	v_and_b32_e32 v176, 0xffff0000, v176
	v_add_f32_e32 v176, v71, v176
	v_lshlrev_b32_e32 v180, 16, v177
	v_and_b32_e32 v177, 0xffff0000, v177
	v_add_f32_e32 v135, v70, v135
	v_add_f32_e32 v177, v73, v177
	v_mul_f32_e32 v176, v176, v176
	v_add_f32_e32 v180, v72, v180
	v_lshlrev_b32_e32 v181, 16, v178
	v_and_b32_e32 v178, 0xffff0000, v178
	v_lshlrev_b32_e32 v182, 16, v179
	v_and_b32_e32 v179, 0xffff0000, v179
	v_fmac_f32_e32 v176, v135, v135
	v_mul_f32_e32 v135, v177, v177
	v_add_f32_e32 v178, v67, v178
	v_add_f32_e32 v179, v69, v179
	v_fmac_f32_e32 v135, v180, v180
	v_add_f32_e32 v181, v66, v181
	v_add_f32_e32 v182, v68, v182
	v_add_f32_e32 v135, v176, v135
	v_mul_f32_e32 v176, v178, v178
	v_mul_f32_e32 v177, v179, v179
	v_fmac_f32_e32 v176, v181, v181
	v_fmac_f32_e32 v177, v182, v182
	v_add_f32_e32 v176, v176, v177
	v_add_f32_e32 v135, v135, v176
	v_add_f32_e32 v134, v134, v135
	ds_bpermute_b32 v135, v197, v134
	s_waitcnt lgkmcnt(0)
	v_add_f32_e32 v204, v134, v135
	v_add_u32_e32 v134, 0x80, v156
	v_ashrrev_i32_e32 v135, 31, v134
	v_lshlrev_b64 v[178:179], 12, v[134:135]
	v_lshlrev_b64 v[134:135], 13, v[134:135]
	v_lshl_add_u64 v[176:177], v[132:133], 0, v[134:135]
	ds_bpermute_b32 v205, v149, v204
	s_waitcnt vmcnt(3)
	v_mov_b32_e32 v180, v242
	v_mov_b32_e32 v181, v243
	v_mov_b32_e32 v182, v244
	v_mov_b32_e32 v183, v245
	s_mov_b64 s[100:101], 0x140000
	v_lshl_add_u64 v[250:251], v[152:153], 0, s[100:101]
	global_load_dwordx4 v[242:245], v[250:251], off
	v_and_b32_e32 v135, 0xffff0000, v180
	v_lshlrev_b32_e32 v134, 16, v180
	v_add_f32_e32 v135, v63, v135
	v_lshlrev_b32_e32 v180, 16, v181
	v_and_b32_e32 v181, 0xffff0000, v181
	v_add_f32_e32 v134, v62, v134
	v_add_f32_e32 v181, v65, v181
	v_mul_f32_e32 v135, v135, v135
	v_add_f32_e32 v180, v64, v180
	v_lshlrev_b32_e32 v184, 16, v182
	v_and_b32_e32 v182, 0xffff0000, v182
	v_lshlrev_b32_e32 v185, 16, v183
	v_and_b32_e32 v183, 0xffff0000, v183
	v_fmac_f32_e32 v135, v134, v134
	v_mul_f32_e32 v134, v181, v181
	v_add_f32_e32 v182, v59, v182
	v_add_f32_e32 v183, v61, v183
	v_fmac_f32_e32 v134, v180, v180
	v_add_f32_e32 v184, v58, v184
	v_add_f32_e32 v185, v60, v185
	v_add_f32_e32 v134, v135, v134
	v_mul_f32_e32 v135, v182, v182
	v_mul_f32_e32 v180, v183, v183
	v_fmac_f32_e32 v135, v184, v184
	v_fmac_f32_e32 v180, v185, v185
	v_add_f32_e32 v135, v135, v180
	v_add_f32_e32 v134, v134, v135
	s_waitcnt vmcnt(3)
	v_mov_b32_e32 v180, v246
	v_mov_b32_e32 v181, v247
	v_mov_b32_e32 v182, v248
	v_mov_b32_e32 v183, v249
	s_mov_b64 s[100:101], 0x140000
	v_lshl_add_u64 v[250:251], v[152:153], 0, s[100:101]
	global_load_dwordx4 v[246:249], v[250:251], off offset:256
	v_lshlrev_b32_e32 v135, 16, v180
	v_and_b32_e32 v180, 0xffff0000, v180
	v_add_f32_e32 v180, v55, v180
	v_lshlrev_b32_e32 v184, 16, v181
	v_and_b32_e32 v181, 0xffff0000, v181
	v_add_f32_e32 v135, v54, v135
	v_add_f32_e32 v181, v57, v181
	v_mul_f32_e32 v180, v180, v180
	v_add_f32_e32 v184, v56, v184
	v_lshlrev_b32_e32 v185, 16, v182
	v_and_b32_e32 v182, 0xffff0000, v182
	v_lshlrev_b32_e32 v186, 16, v183
	v_and_b32_e32 v183, 0xffff0000, v183
	v_fmac_f32_e32 v180, v135, v135
	v_mul_f32_e32 v135, v181, v181
	v_add_f32_e32 v182, v51, v182
	v_add_f32_e32 v183, v53, v183
	v_fmac_f32_e32 v135, v184, v184
	v_add_f32_e32 v185, v50, v185
	v_add_f32_e32 v186, v52, v186
	v_add_f32_e32 v135, v180, v135
	v_mul_f32_e32 v180, v182, v182
	v_mul_f32_e32 v181, v183, v183
	v_fmac_f32_e32 v180, v185, v185
	v_fmac_f32_e32 v181, v186, v186
	v_add_f32_e32 v180, v180, v181
	v_add_f32_e32 v135, v135, v180
	v_add_f32_e32 v134, v134, v135
	ds_bpermute_b32 v135, v197, v134
	s_waitcnt lgkmcnt(0)
	v_add_f32_e32 v206, v134, v135
	v_add_u32_e32 v134, 0x90, v156
	v_ashrrev_i32_e32 v135, 31, v134
	v_lshlrev_b64 v[182:183], 12, v[134:135]
	v_lshlrev_b64 v[134:135], 13, v[134:135]
	v_lshl_add_u64 v[180:181], v[132:133], 0, v[134:135]
	ds_bpermute_b32 v207, v149, v206
	s_waitcnt vmcnt(3)
	v_mov_b32_e32 v184, v220
	v_mov_b32_e32 v185, v221
	v_mov_b32_e32 v186, v222
	v_mov_b32_e32 v187, v223
	s_mov_b64 s[100:101], 0x160000
	v_lshl_add_u64 v[250:251], v[152:153], 0, s[100:101]
	global_load_dwordx4 v[220:223], v[250:251], off
	v_and_b32_e32 v135, 0xffff0000, v184
	v_lshlrev_b32_e32 v134, 16, v184
	v_add_f32_e32 v135, v47, v135
	v_lshlrev_b32_e32 v184, 16, v185
	v_and_b32_e32 v185, 0xffff0000, v185
	v_add_f32_e32 v134, v46, v134
	v_add_f32_e32 v185, v49, v185
	v_mul_f32_e32 v135, v135, v135
	v_add_f32_e32 v184, v48, v184
	v_lshlrev_b32_e32 v188, 16, v186
	v_and_b32_e32 v186, 0xffff0000, v186
	v_lshlrev_b32_e32 v189, 16, v187
	v_and_b32_e32 v187, 0xffff0000, v187
	v_fmac_f32_e32 v135, v134, v134
	v_mul_f32_e32 v134, v185, v185
	v_add_f32_e32 v186, v43, v186
	v_add_f32_e32 v187, v45, v187
	v_fmac_f32_e32 v134, v184, v184
	v_add_f32_e32 v188, v42, v188
	v_add_f32_e32 v189, v44, v189
	v_add_f32_e32 v134, v135, v134
	v_mul_f32_e32 v135, v186, v186
	v_mul_f32_e32 v184, v187, v187
	v_fmac_f32_e32 v135, v188, v188
	v_fmac_f32_e32 v184, v189, v189
	v_add_f32_e32 v135, v135, v184
	v_add_f32_e32 v134, v134, v135
	s_waitcnt vmcnt(3)
	v_mov_b32_e32 v184, v224
	v_mov_b32_e32 v185, v225
	v_mov_b32_e32 v186, v226
	v_mov_b32_e32 v187, v227
	s_mov_b64 s[100:101], 0x160000
	v_lshl_add_u64 v[250:251], v[152:153], 0, s[100:101]
	global_load_dwordx4 v[224:227], v[250:251], off offset:256
	v_lshlrev_b32_e32 v135, 16, v184
	v_and_b32_e32 v184, 0xffff0000, v184
	v_add_f32_e32 v184, v39, v184
	v_lshlrev_b32_e32 v188, 16, v185
	v_and_b32_e32 v185, 0xffff0000, v185
	v_add_f32_e32 v135, v38, v135
	v_add_f32_e32 v185, v41, v185
	v_mul_f32_e32 v184, v184, v184
	v_add_f32_e32 v188, v40, v188
	v_lshlrev_b32_e32 v189, 16, v186
	v_and_b32_e32 v186, 0xffff0000, v186
	v_lshlrev_b32_e32 v190, 16, v187
	v_and_b32_e32 v187, 0xffff0000, v187
	v_fmac_f32_e32 v184, v135, v135
	v_mul_f32_e32 v135, v185, v185
	v_add_f32_e32 v186, v35, v186
	v_add_f32_e32 v187, v37, v187
	v_fmac_f32_e32 v135, v188, v188
	v_add_f32_e32 v189, v34, v189
	v_add_f32_e32 v190, v36, v190
	v_add_f32_e32 v135, v184, v135
	v_mul_f32_e32 v184, v186, v186
	v_mul_f32_e32 v185, v187, v187
	v_fmac_f32_e32 v184, v189, v189
	v_fmac_f32_e32 v185, v190, v190
	v_add_f32_e32 v184, v184, v185
	v_add_f32_e32 v135, v135, v184
	v_add_f32_e32 v134, v134, v135
	ds_bpermute_b32 v135, v197, v134
	s_waitcnt lgkmcnt(0)
	v_add_f32_e32 v208, v134, v135
	v_add_u32_e32 v134, 0xa0, v156
	v_ashrrev_i32_e32 v135, 31, v134
	v_lshlrev_b64 v[186:187], 12, v[134:135]
	v_lshlrev_b64 v[134:135], 13, v[134:135]
	v_lshl_add_u64 v[184:185], v[132:133], 0, v[134:135]
	ds_bpermute_b32 v209, v149, v208
	s_waitcnt vmcnt(3)
	v_mov_b32_e32 v188, v242
	v_mov_b32_e32 v189, v243
	v_mov_b32_e32 v190, v244
	v_mov_b32_e32 v191, v245
	v_and_b32_e32 v135, 0xffff0000, v188
	v_lshlrev_b32_e32 v134, 16, v188
	v_add_f32_e32 v135, v31, v135
	v_lshlrev_b32_e32 v188, 16, v189
	v_and_b32_e32 v189, 0xffff0000, v189
	v_add_f32_e32 v134, v30, v134
	v_add_f32_e32 v189, v33, v189
	v_mul_f32_e32 v135, v135, v135
	v_add_f32_e32 v188, v32, v188
	v_lshlrev_b32_e32 v210, 16, v190
	v_and_b32_e32 v190, 0xffff0000, v190
	v_lshlrev_b32_e32 v211, 16, v191
	v_and_b32_e32 v191, 0xffff0000, v191
	v_fmac_f32_e32 v135, v134, v134
	v_mul_f32_e32 v134, v189, v189
	v_add_f32_e32 v190, v27, v190
	v_add_f32_e32 v191, v29, v191
	v_fmac_f32_e32 v134, v188, v188
	v_add_f32_e32 v210, v26, v210
	v_add_f32_e32 v211, v28, v211
	v_add_f32_e32 v134, v135, v134
	v_mul_f32_e32 v135, v190, v190
	v_mul_f32_e32 v188, v191, v191
	v_fmac_f32_e32 v135, v210, v210
	v_fmac_f32_e32 v188, v211, v211
	v_add_f32_e32 v135, v135, v188
	v_add_f32_e32 v134, v134, v135
	s_waitcnt vmcnt(2)
	v_mov_b32_e32 v188, v246
	v_mov_b32_e32 v189, v247
	v_mov_b32_e32 v190, v248
	v_mov_b32_e32 v191, v249
	v_lshlrev_b32_e32 v135, 16, v188
	v_and_b32_e32 v188, 0xffff0000, v188
	v_add_f32_e32 v188, v23, v188
	v_lshlrev_b32_e32 v210, 16, v189
	v_and_b32_e32 v189, 0xffff0000, v189
	v_add_f32_e32 v135, v22, v135
	v_add_f32_e32 v189, v25, v189
	v_mul_f32_e32 v188, v188, v188
	v_add_f32_e32 v210, v24, v210
	v_lshlrev_b32_e32 v211, 16, v190
	v_and_b32_e32 v190, 0xffff0000, v190
	v_lshlrev_b32_e32 v212, 16, v191
	v_and_b32_e32 v191, 0xffff0000, v191
	v_fmac_f32_e32 v188, v135, v135
	v_mul_f32_e32 v135, v189, v189
	v_add_f32_e32 v190, v19, v190
	v_add_f32_e32 v191, v21, v191
	v_fmac_f32_e32 v135, v210, v210
	v_add_f32_e32 v211, v18, v211
	v_add_f32_e32 v212, v20, v212
	v_add_f32_e32 v135, v188, v135
	v_mul_f32_e32 v188, v190, v190
	v_mul_f32_e32 v189, v191, v191
	v_fmac_f32_e32 v188, v211, v211
	v_fmac_f32_e32 v189, v212, v212
	v_add_f32_e32 v188, v188, v189
	v_add_f32_e32 v135, v135, v188
	v_add_f32_e32 v134, v134, v135
	ds_bpermute_b32 v135, v197, v134
	s_waitcnt lgkmcnt(0)
	v_add_f32_e32 v210, v134, v135
	v_add_u32_e32 v134, 0xb0, v156
	v_ashrrev_i32_e32 v135, 31, v134
	v_lshlrev_b64 v[190:191], 12, v[134:135]
	v_lshlrev_b64 v[134:135], 13, v[134:135]
	v_lshl_add_u64 v[188:189], v[132:133], 0, v[134:135]
	ds_bpermute_b32 v211, v149, v210
	s_waitcnt vmcnt(1)
	v_mov_b32_e32 v132, v220
	v_mov_b32_e32 v133, v221
	v_mov_b32_e32 v134, v222
	v_mov_b32_e32 v135, v223
	v_lshlrev_b32_e32 v212, 16, v132
	v_and_b32_e32 v132, 0xffff0000, v132
	v_lshlrev_b32_e32 v213, 16, v133
	v_and_b32_e32 v133, 0xffff0000, v133
	v_add_f32_e32 v132, v15, v132
	v_add_f32_e32 v133, v17, v133
	v_add_f32_e32 v212, v14, v212
	v_add_f32_e32 v213, v16, v213
	v_lshlrev_b32_e32 v216, 16, v134
	v_and_b32_e32 v134, 0xffff0000, v134
	v_lshlrev_b32_e32 v217, 16, v135
	v_and_b32_e32 v135, 0xffff0000, v135
	v_mul_f32_e32 v132, v132, v132
	v_mul_f32_e32 v133, v133, v133
	v_add_f32_e32 v134, v11, v134
	v_add_f32_e32 v135, v13, v135
	v_fmac_f32_e32 v132, v212, v212
	v_fmac_f32_e32 v133, v213, v213
	v_add_f32_e32 v216, v10, v216
	v_add_f32_e32 v217, v12, v217
	v_add_f32_e32 v132, v132, v133
	v_mul_f32_e32 v133, v134, v134
	v_mul_f32_e32 v134, v135, v135
	v_fmac_f32_e32 v133, v216, v216
	v_fmac_f32_e32 v134, v217, v217
	v_add_f32_e32 v133, v133, v134
	v_add_f32_e32 v212, v132, v133
	s_waitcnt vmcnt(0)
	v_mov_b32_e32 v132, v224
	v_mov_b32_e32 v133, v225
	v_mov_b32_e32 v134, v226
	v_mov_b32_e32 v135, v227
	v_lshlrev_b32_e32 v213, 16, v132
	v_and_b32_e32 v132, 0xffff0000, v132
	v_lshlrev_b32_e32 v216, 16, v133
	v_and_b32_e32 v133, 0xffff0000, v133
	v_add_f32_e32 v132, v7, v132
	v_add_f32_e32 v133, v9, v133
	v_add_f32_e32 v213, v6, v213
	v_add_f32_e32 v216, v8, v216
	v_lshlrev_b32_e32 v217, 16, v134
	v_and_b32_e32 v134, 0xffff0000, v134
	v_lshlrev_b32_e32 v218, 16, v135
	v_and_b32_e32 v135, 0xffff0000, v135
	v_mul_f32_e32 v132, v132, v132
	v_mul_f32_e32 v133, v133, v133
	v_add_f32_e32 v134, v3, v134
	v_add_f32_e32 v135, v5, v135
	v_fmac_f32_e32 v132, v213, v213
	v_fmac_f32_e32 v133, v216, v216
	v_add_f32_e32 v217, v2, v217
	v_add_f32_e32 v218, v4, v218
	v_add_f32_e32 v132, v132, v133
	v_mul_f32_e32 v133, v134, v134
	v_mul_f32_e32 v134, v135, v135
	v_fmac_f32_e32 v133, v217, v217
	v_fmac_f32_e32 v134, v218, v218
	v_add_f32_e32 v133, v133, v134
	v_add_f32_e32 v132, v132, v133
	v_add_f32_e32 v132, v212, v132
	ds_bpermute_b32 v133, v197, v132
	s_waitcnt lgkmcnt(0)
	v_add_f32_e32 v197, v132, v133
	ds_bpermute_b32 v212, v149, v197
	s_and_saveexec_b64 s[22:23], vcc
	s_xor_b64 s[22:23], exec, s[22:23]
	s_cbranch_execz .LBB0_1363
	v_cmp_lt_i32_e32 vcc, 2, v192
	s_and_saveexec_b64 s[24:25], vcc
	s_xor_b64 s[24:25], exec, s[24:25]
	v_add_f32_e32 v213, v210, v211
	s_andn2_saveexec_b64 s[24:25], s[24:25]
	v_add_f32_e32 v213, v206, v207
	s_or_b64 exec, exec, s[24:25]
